# MLA K/V/rope-key tile global loads issued one tile earlier (right after the previous staging writes), stray tail loads drained at loop exit
# speedup vs baseline: 1.0018x; 1.0018x over previous
; #define SBAR() __builtin_amdgcn_sched_barrier(0)
; template <int DVB> __device__ __forceinline__ int v_st(int k, int c) { const int kk = (k & ~0xC) | ((k & 4) << 1) | ((k & 8) >> 1); return ((kk >> 3) * DVB + (c >> 5)) * 512 + ((kk & 7) * 32 + (c & 31)) * 2; }
; __device__ __forceinline__ int v_rd_base(int lane) { return ((lane & 3) << 3) | (((lane >> 2) & 3) << 6) | (((lane >> 4) & 1) << 5) | (((lane >> 5) & 1) << 8); }
; #define SLOAD2(k0) do { s_kn = *reinterpret_cast<const bf16x8*>(Kn + (size_t)((k0) + kn_r) * 1024 + kn_c); s_kr = *reinterpret_cast<const bf16x8*>(Kr + (size_t)((k0) + kr_r) * 32 + kr_c); \
;     s_v = *reinterpret_cast<const bf16x8*>(Vh + (size_t)((k0) + kn_r) * 1024 + kn_c); } while (0)
; __device__ __forceinline__ void attn_mla2(const bf16* __restrict__ Q0, const bf16* __restrict__ Q1, const bf16* __restrict__ Kn, const bf16* __restrict__ Kr, const bf16* __restrict__ Vh, ...
;     ...
;     const int kn_r = tid >> 3, kn_c = (tid & 7) * 8, kn_st = kn_r * 144 + kn_c * 2;
;     const int kr_r = (tid >> 2) & 63, kr_c = (tid & 3) * 8, kr_st = kr_r * 80 + kr_c * 2;
;     const int vst0 = v_st<2>(kn_r, kn_c);
;     const int vb0 = (int)(uintptr_t)(lds + V_OFF) + v_rd_base(lane);
;     bf16x8 s_kn, s_kr, s_v;
;     ...
;     constexpr int NT = SEQ / 64;
;     SLOAD2(0); SWRITE2(0); __syncthreads();
;     int cur = 0;
;     for (int t = 0; t < NT; ++t) {
;         const char* buf = lds + cur;
;         f32x16 pa0 = f32x16{}, pa1 = f32x16{}, pb0 = f32x16{}, pb1 = f32x16{};
;         {
;             const char* kb = buf + KN_OFF + r32 * 144 + hi * 16; const char* kr = buf + KR_OFF + r32 * 80 + hi * 16;
;     ...
;             bf16x8 c0 = KLD0(0), c1 = KLD1(0);
; #pragma unroll
;             for (int d0 = 0; d0 < 6; ++d0) {
;                 bf16x8 n0 = c0, n1 = c1;
;                 if (d0 + 1 < 6) { n0 = KLD0(d0 + 1); n1 = KLD1(d0 + 1); }
;                 pa0 = __builtin_amdgcn_mfma_f32_32x32x16_bf16(c0, q0[d0], pa0, 0, 0, 0); pb0 = __builtin_amdgcn_mfma_f32_32x32x16_bf16(c0, q1[d0], pb0, 0, 0, 0);
;                 pa1 = __builtin_amdgcn_mfma_f32_32x32x16_bf16(c1, q0[d0], pa1, 0, 0, 0); pb1 = __builtin_amdgcn_mfma_f32_32x32x16_bf16(c1, q1[d0], pb1, 0, 0, 0);
;                 SBAR(); c0 = n0; c1 = n1;
;             }
;     ...
;         }
;         if (t + 1 < NT) SLOAD2((t + 1) * 64);
.LBB0_1628:
	s_or_b64 exec, exec, s[28:29]
	v_and_or_b32 v5, v16, 8, v15
	v_lshrrev_b32_e32 v5, 2, v5
	v_lshrrev_b32_e32 v15, 5, v17
	v_or_b32_e32 v5, v5, v15
	v_and_or_b32 v13, v13, 4, v14
	v_lshlrev_b32_e32 v13, 6, v13
	v_and_b32_e32 v14, 48, v184
	v_lshl_add_u32 v5, v5, 9, 0
	s_add_i32 s17, 0, 0x3800
	v_add3_u32 v5, v5, v13, v14
	s_movk_i32 s16, 0x118
	s_cmp_lg_u32 s17, -1
	ds_write_b128 v5, v[0:3] offset:14336
	v_and_or_b32 v0, v7, s16, v12
	s_cselect_b32 s17, s17, 0
	v_and_b32_e32 v184, 0xfc0, v10
	v_add3_u32 v248, v11, s17, v0
	v_lshl_add_u64 v[0:1], s[14:15], 0, v[184:185]
	v_mov_b32_e32 v7, v185
	v_readlane_b32 s14, v255, 31
	v_lshl_add_u64 v[0:1], v[0:1], 0, v[6:7]
	v_readlane_b32 s15, v255, 32
	v_mov_b32_e32 v5, v185
	v_mov_b32_e32 v240, 0x358637bd
	v_lshl_add_u64 v[192:193], s[14:15], 0, v[0:1]
	v_and_b32_e32 v0, 0xff, v241
	v_lshlrev_b32_e32 v0, 4, v0
	v_lshlrev_b32_e32 v1, 3, v241
	v_sub_u32_e32 v0, v1, v0
	v_ashrrev_i32_e32 v1, 31, v0
	v_lshl_add_u64 v[192:193], v[192:193], 0, v[0:1]
	v_lshl_add_u64 v[0:1], s[12:13], 0, v[8:9]
	v_or_b32_e32 v0, s72, v0
	v_readlane_b32 s12, v254, 10
	v_lshl_add_u64 v[0:1], v[0:1], 0, v[4:5]
	v_readlane_b32 s14, v254, 12
	v_readlane_b32 s15, v254, 13
	s_mov_b32 s16, 0
	s_mov_b64 s[36:37], 0x20000
	v_lshl_add_u64 v[194:195], s[14:15], 0, v[0:1]
	v_mov_b32_e32 v0, 0
	s_movk_i32 s14, 0x7f
	v_mov_b32_e32 v1, v0
	v_mov_b32_e32 v2, v0
	v_mov_b32_e32 v3, v0
	v_mov_b32_e32 v4, v0
	v_mov_b32_e32 v5, v0
	v_mov_b32_e32 v6, v0
	v_mov_b32_e32 v7, v0
	v_mov_b32_e32 v8, v0
	v_mov_b32_e32 v9, v0
	v_mov_b32_e32 v10, v0
	v_mov_b32_e32 v11, v0
	v_mov_b32_e32 v12, v0
	v_mov_b32_e32 v13, v0
	v_mov_b32_e32 v14, v0
	v_mov_b32_e32 v15, v0
	v_mov_b32_e32 v16, v0
	v_mov_b32_e32 v17, v0
	v_mov_b32_e32 v18, v0
	v_mov_b32_e32 v19, v0
	v_mov_b32_e32 v20, v0
	v_mov_b32_e32 v21, v0
	v_mov_b32_e32 v22, v0
	v_mov_b32_e32 v23, v0
	v_mov_b32_e32 v24, v0
	v_mov_b32_e32 v25, v0
	v_mov_b32_e32 v26, v0
	v_mov_b32_e32 v27, v0
	v_mov_b32_e32 v28, v0
	v_mov_b32_e32 v29, v0
	v_mov_b32_e32 v30, v0
	v_mov_b32_e32 v31, v0
	v_mov_b32_e32 v32, v0
	v_mov_b32_e32 v33, v0
	v_mov_b32_e32 v34, v0
	v_mov_b32_e32 v35, v0
	v_mov_b32_e32 v36, v0
	v_mov_b32_e32 v37, v0
	v_mov_b32_e32 v38, v0
	v_mov_b32_e32 v39, v0
	v_mov_b32_e32 v40, v0
	v_mov_b32_e32 v41, v0
	v_mov_b32_e32 v42, v0
	v_mov_b32_e32 v43, v0
	v_mov_b32_e32 v44, v0
	v_mov_b32_e32 v45, v0
	v_mov_b32_e32 v46, v0
	v_mov_b32_e32 v47, v0
	v_mov_b32_e32 v48, v0
	v_mov_b32_e32 v49, v0
	v_mov_b32_e32 v50, v0
	v_mov_b32_e32 v51, v0
	v_mov_b32_e32 v52, v0
	v_mov_b32_e32 v53, v0
	v_mov_b32_e32 v54, v0
	v_mov_b32_e32 v55, v0
	v_mov_b32_e32 v56, v0
	v_mov_b32_e32 v57, v0
	v_mov_b32_e32 v58, v0
	v_mov_b32_e32 v59, v0
	v_mov_b32_e32 v60, v0
	v_mov_b32_e32 v61, v0
	v_mov_b32_e32 v62, v0
	v_mov_b32_e32 v63, v0
	v_mov_b32_e32 v190, v0
	v_mov_b32_e32 v191, v0
	s_waitcnt lgkmcnt(0)
	s_barrier
	v_readlane_b32 s13, v254, 11
	v_lshl_add_u64 v[176:177], v[194:195], 0, s[2:3]
	s_mov_b32 s12, 0x8e20000
	v_add_co_u32_e32 v178, vcc, s12, v176
	s_mov_b32 s12, 0xae20000
	s_nop 0
	v_addc_co_u32_e32 v179, vcc, 0, v177, vcc
	v_add_co_u32_e32 v176, vcc, s12, v176
	s_nop 1
	v_addc_co_u32_e32 v177, vcc, 0, v177, vcc
	global_load_dwordx4 v[180:183], v[178:179], off
	global_load_dwordx4 v[176:179], v[176:177], off
	v_lshl_add_u64 v[186:187], v[192:193], 0, s[2:3]
	global_load_dwordx2 v[186:187], v[186:187], off
.LBB0_1629:
	s_add_i32 s12, s16, 0
	v_add3_u32 v184, s12, v246, v244
	v_add3_u32 v188, s12, v245, v244
	ds_read_b128 v[196:199], v184
	ds_read_b128 v[200:203], v184 offset:32
	ds_read_b128 v[204:207], v184 offset:64
	ds_read_b128 v[208:211], v184 offset:96
	ds_read_b128 v[212:215], v188 offset:9216
	ds_read_b128 v[216:219], v188 offset:9248
	ds_read_b128 v[220:223], v184 offset:4608
	ds_read_b128 v[224:227], v184 offset:4640
	ds_read_b128 v[228:231], v184 offset:4672
	ds_read_b128 v[232:235], v184 offset:4704
	ds_read_b128 v[236:239], v188 offset:11776
	ds_read_b128 v[250:253], v188 offset:11808
	s_waitcnt lgkmcnt(11)
	v_mfma_f32_32x32x16_bf16 v[96:111], v[196:199], v[160:163], 0
	s_sub_i32 s15, 0, s16
	v_ashrrev_i32_e32 v80, 3, v241
	v_and_b32_e32 v81, 7, v241
	s_waitcnt lgkmcnt(10)
	v_mfma_f32_32x32x16_bf16 v[96:111], v[200:203], v[168:171], v[96:111]
	v_lshlrev_b32_e32 v82, 4, v81
	v_mul_u32_u24_e32 v184, 0x90, v80
	v_add3_u32 v184, s15, v184, v82
	s_waitcnt lgkmcnt(9)
	v_mfma_f32_32x32x16_bf16 v[96:111], v[204:207], v[156:159], v[96:111]
	v_mul_u32_u24_e32 v189, 0x50, v80
	v_lshlrev_b32_e32 v83, 3, v81
	v_add3_u32 v189, s15, v189, v83
	s_waitcnt lgkmcnt(8)
	v_mfma_f32_32x32x16_bf16 v[96:111], v[208:211], v[144:147], v[96:111]
	v_bfe_u32 v83, v241, 3, 2
	v_and_b32_e32 v82, 48, v82
	v_lshlrev_b32_e32 v84, 1, v80
	s_waitcnt lgkmcnt(7)
	v_mfma_f32_32x32x16_bf16 v[96:111], v[212:215], v[140:143], v[96:111]
	v_and_b32_e32 v85, 0x1fffff0, v80
	v_and_b32_e32 v84, 8, v84
	v_or3_b32 v81, v84, v85, v81
	s_waitcnt lgkmcnt(6)
; #define SBAR() __builtin_amdgcn_sched_barrier(0)
; #define SLOAD2(k0) do { s_kn = *reinterpret_cast<const bf16x8*>(Kn + (size_t)((k0) + kn_r) * 1024 + kn_c); s_kr = *reinterpret_cast<const bf16x8*>(Kr + (size_t)((k0) + kr_r) * 32 + kr_c); \
;     s_v = *reinterpret_cast<const bf16x8*>(Vh + (size_t)((k0) + kn_r) * 1024 + kn_c); } while (0)
; __device__ __forceinline__ void attn_mla2(const bf16* __restrict__ Q0, const bf16* __restrict__ Q1, const bf16* __restrict__ Kn, const bf16* __restrict__ Kr, const bf16* __restrict__ Vh, ...
;     ...
;         {
;             const char* kb = buf + KN_OFF + r32 * 144 + hi * 16; const char* kr = buf + KR_OFF + r32 * 80 + hi * 16;
;     ...
;             bf16x8 c0 = KLD0(0), c1 = KLD1(0);
; #pragma unroll
;             for (int d0 = 0; d0 < 6; ++d0) {
;                 bf16x8 n0 = c0, n1 = c1;
;                 if (d0 + 1 < 6) { n0 = KLD0(d0 + 1); n1 = KLD1(d0 + 1); }
;                 pa0 = __builtin_amdgcn_mfma_f32_32x32x16_bf16(c0, q0[d0], pa0, 0, 0, 0); pb0 = __builtin_amdgcn_mfma_f32_32x32x16_bf16(c0, q1[d0], pb0, 0, 0, 0);
;                 pa1 = __builtin_amdgcn_mfma_f32_32x32x16_bf16(c1, q0[d0], pa1, 0, 0, 0); pb1 = __builtin_amdgcn_mfma_f32_32x32x16_bf16(c1, q1[d0], pb1, 0, 0, 0);
;                 SBAR(); c0 = n0; c1 = n1;
;             }
;     ...
;         }
;         if (t + 1 < NT) SLOAD2((t + 1) * 64);
;         bf16x8 fa0, fa1, fa2, fa3, fb0, fb1, fb2, fb3;
;         {   float ps = 0.f;
; #pragma unroll
;             for (int r = 0; r < 16; ++r) { pa0[r] = __builtin_amdgcn_exp2f(pa0[r]); pa1[r] = __builtin_amdgcn_exp2f(pa1[r]);     ps += pa0[r] + pa1[r]; }
;             l0 += ps; PK4(pa0, 0, fa0); PK4(pa0, 8, fa1); PK4(pa1, 0, fa2); PK4(pa1, 8, fa3); }
;         {   float ps = 0.f;
; #pragma unroll
;             for (int r = 0; r < 16; ++r) { pb0[r] = __builtin_amdgcn_exp2f(pb0[r]); pb1[r] = __builtin_amdgcn_exp2f(pb1[r]); ps += pb0[r] + pb1[r]; }
;             l1 += ps; PK4(pb0, 0, fb0); PK4(pb0, 8, fb1); PK4(pb1, 0, fb2); PK4(pb1, 8, fb3); }
	v_mfma_f32_32x32x16_bf16 v[96:111], v[216:219], v[128:131], v[96:111]
	v_lshrrev_b32_e32 v80, 1, v80
	v_lshlrev_b32_e32 v81, 7, v81
	v_and_b32_e32 v81, 0xfffffe00, v81
	v_and_or_b32 v83, v80, 4, v83
	v_lshlrev_b32_e32 v83, 6, v83
	v_mfma_f32_32x32x16_bf16 v[64:79], v[196:199], v[164:167], 0
	v_add_u32_e32 v80, s15, v81
	v_add3_u32 v188, v80, v83, v82
	v_lshl_add_u64 v[192:193], v[192:193], 0, s[30:31]
	v_lshl_add_u64 v[194:195], v[194:195], 0, s[36:37]
	s_nop 0
	v_mfma_f32_32x32x16_bf16 v[64:79], v[200:203], v[172:175], v[64:79]
	v_exp_f32_e32 v96, v96
	v_exp_f32_e32 v97, v97
	v_add_f32_e32 v190, v190, v96
	v_exp_f32_e32 v98, v98
	v_add_f32_e32 v190, v190, v97
	v_mfma_f32_32x32x16_bf16 v[64:79], v[204:207], v[152:155], v[64:79]
	v_exp_f32_e32 v99, v99
	v_add_f32_e32 v190, v190, v98
	v_exp_f32_e32 v100, v100
	v_add_f32_e32 v190, v190, v99
	v_exp_f32_e32 v101, v101
	v_mfma_f32_32x32x16_bf16 v[64:79], v[208:211], v[148:151], v[64:79]
	v_add_f32_e32 v190, v190, v100
	v_exp_f32_e32 v102, v102
	v_add_f32_e32 v190, v190, v101
	v_exp_f32_e32 v103, v103
	v_add_f32_e32 v190, v190, v102
	v_exp_f32_e32 v104, v104
	v_mfma_f32_32x32x16_bf16 v[64:79], v[212:215], v[136:139], v[64:79]
	v_add_f32_e32 v190, v190, v103
	v_exp_f32_e32 v105, v105
	v_add_f32_e32 v190, v190, v104
	v_exp_f32_e32 v106, v106
	v_add_f32_e32 v190, v190, v105
	v_mfma_f32_32x32x16_bf16 v[64:79], v[216:219], v[132:135], v[64:79]
	v_exp_f32_e32 v107, v107
	v_add_f32_e32 v190, v190, v106
	v_exp_f32_e32 v108, v108
	v_add_f32_e32 v190, v190, v107
	v_exp_f32_e32 v109, v109
	v_and_b32_e32 v213, 32, v241
	v_mad_u32_u24 v212, v213, 24, v248
	v_add_u32_e32 v212, s16, v212
	s_waitcnt lgkmcnt(5)
	v_mfma_f32_32x32x16_bf16 v[112:127], v[220:223], v[160:163], 0
	v_add_f32_e32 v190, v190, v108
	v_exp_f32_e32 v110, v110
	v_add_f32_e32 v190, v190, v109
	v_exp_f32_e32 v111, v111
	v_add_f32_e32 v190, v190, v110
	v_add_f32_e32 v190, v190, v111
	s_waitcnt lgkmcnt(4)
	v_mfma_f32_32x32x16_bf16 v[112:127], v[224:227], v[168:171], v[112:127]
	v_exp_f32_e32 v64, v64
	v_exp_f32_e32 v65, v65
	v_add_f32_e32 v191, v191, v64
	v_exp_f32_e32 v66, v66
	v_add_f32_e32 v191, v191, v65
	s_waitcnt lgkmcnt(3)
	v_mfma_f32_32x32x16_bf16 v[112:127], v[228:231], v[156:159], v[112:127]
	v_exp_f32_e32 v67, v67
	v_add_f32_e32 v191, v191, v66
	v_exp_f32_e32 v68, v68
	v_add_f32_e32 v191, v191, v67
	v_exp_f32_e32 v69, v69
	s_waitcnt lgkmcnt(2)
	v_mfma_f32_32x32x16_bf16 v[112:127], v[232:235], v[144:147], v[112:127]
	v_add_f32_e32 v191, v191, v68
	v_exp_f32_e32 v70, v70
	v_add_f32_e32 v191, v191, v69
	v_exp_f32_e32 v71, v71
	v_add_f32_e32 v191, v191, v70
	v_exp_f32_e32 v72, v72
	s_waitcnt lgkmcnt(1)
	v_mfma_f32_32x32x16_bf16 v[112:127], v[236:239], v[140:143], v[112:127]
	v_add_f32_e32 v191, v191, v71
	v_exp_f32_e32 v73, v73
	v_add_f32_e32 v191, v191, v72
	v_exp_f32_e32 v74, v74
	v_add_f32_e32 v191, v191, v73
	s_waitcnt lgkmcnt(0)
	v_mfma_f32_32x32x16_bf16 v[112:127], v[250:253], v[128:131], v[112:127]
	v_exp_f32_e32 v75, v75
	v_add_f32_e32 v191, v191, v74
	v_exp_f32_e32 v76, v76
	v_add_f32_e32 v191, v191, v75
	v_exp_f32_e32 v77, v77
	v_mfma_f32_32x32x16_bf16 v[80:95], v[220:223], v[164:167], 0
	v_add_f32_e32 v191, v191, v76
	v_exp_f32_e32 v78, v78
	v_add_f32_e32 v191, v191, v77
	v_exp_f32_e32 v79, v79
	v_add_f32_e32 v191, v191, v78
	v_add_f32_e32 v191, v191, v79
	v_mfma_f32_32x32x16_bf16 v[80:95], v[224:227], v[172:175], v[80:95]
	v_cvt_pk_bf16_f32 v196, v96, v97
	v_cvt_pk_bf16_f32 v197, v98, v99
	v_cvt_pk_bf16_f32 v198, v100, v101
	v_cvt_pk_bf16_f32 v199, v102, v103
	v_cvt_pk_bf16_f32 v200, v104, v105
	v_cvt_pk_bf16_f32 v201, v106, v107
	v_cvt_pk_bf16_f32 v202, v108, v109
	v_cvt_pk_bf16_f32 v203, v110, v111
	v_mfma_f32_32x32x16_bf16 v[80:95], v[228:231], v[152:155], v[80:95]
	ds_read_b64_tr_b16 v[96:97], v212 offset:0
	ds_read_b64_tr_b16 v[98:99], v212 offset:256
	ds_read_b64_tr_b16 v[100:101], v212 offset:2048
	ds_read_b64_tr_b16 v[102:103], v212 offset:2304
	ds_read_b64_tr_b16 v[104:105], v212 offset:512
	ds_read_b64_tr_b16 v[106:107], v212 offset:768
	ds_read_b64_tr_b16 v[108:109], v212 offset:2560
	ds_read_b64_tr_b16 v[110:111], v212 offset:2816
	v_mfma_f32_32x32x16_bf16 v[80:95], v[232:235], v[148:151], v[80:95]
	v_cvt_pk_bf16_f32 v204, v64, v65
	v_cvt_pk_bf16_f32 v205, v66, v67
	v_cvt_pk_bf16_f32 v206, v68, v69
	v_cvt_pk_bf16_f32 v207, v70, v71
	v_cvt_pk_bf16_f32 v208, v72, v73
	v_cvt_pk_bf16_f32 v209, v74, v75
	v_cvt_pk_bf16_f32 v210, v76, v77
	v_cvt_pk_bf16_f32 v211, v78, v79
	v_mfma_f32_32x32x16_bf16 v[80:95], v[236:239], v[136:139], v[80:95]
	ds_read_b64_tr_b16 v[64:65], v212 offset:4096
	ds_read_b64_tr_b16 v[66:67], v212 offset:4352
	ds_read_b64_tr_b16 v[68:69], v212 offset:6144
	ds_read_b64_tr_b16 v[70:71], v212 offset:6400
	ds_read_b64_tr_b16 v[72:73], v212 offset:4608
	ds_read_b64_tr_b16 v[74:75], v212 offset:4864
	ds_read_b64_tr_b16 v[76:77], v212 offset:6656
	ds_read_b64_tr_b16 v[78:79], v212 offset:6912
	v_mfma_f32_32x32x16_bf16 v[80:95], v[250:253], v[132:135], v[80:95]
	v_exp_f32_e32 v112, v112
	v_exp_f32_e32 v113, v113
	v_add_f32_e32 v190, v190, v112
	v_exp_f32_e32 v114, v114
	v_add_f32_e32 v190, v190, v113
	s_waitcnt lgkmcnt(8)
; __device__ __forceinline__ void attn_mla2(const bf16* __restrict__ Q0, const bf16* __restrict__ Q1, const bf16* __restrict__ Kn, const bf16* __restrict__ Kr, const bf16* __restrict__ Vh, ...
;     ...
;     for (int t = 0; t < NT; ++t) {
;         const char* buf = lds + cur;
;         f32x16 pa0 = f32x16{}, pa1 = f32x16{}, pb0 = f32x16{}, pb1 = f32x16{};
;         {
;             const char* kb = buf + KN_OFF + r32 * 144 + hi * 16; const char* kr = buf + KR_OFF + r32 * 80 + hi * 16;
;     ...
;             bf16x8 c0 = KLD0(0), c1 = KLD1(0);
; #pragma unroll
;             for (int d0 = 0; d0 < 6; ++d0) {
;                 bf16x8 n0 = c0, n1 = c1;
;                 if (d0 + 1 < 6) { n0 = KLD0(d0 + 1); n1 = KLD1(d0 + 1); }
;                 pa0 = __builtin_amdgcn_mfma_f32_32x32x16_bf16(c0, q0[d0], pa0, 0, 0, 0); pb0 = __builtin_amdgcn_mfma_f32_32x32x16_bf16(c0, q1[d0], pb0, 0, 0, 0);
;                 pa1 = __builtin_amdgcn_mfma_f32_32x32x16_bf16(c1, q0[d0], pa1, 0, 0, 0); pb1 = __builtin_amdgcn_mfma_f32_32x32x16_bf16(c1, q1[d0], pb1, 0, 0, 0);
;                 SBAR(); c0 = n0; c1 = n1;
;             }
;     ...
;         }
;         if (t + 1 < NT) SLOAD2((t + 1) * 64);
;         bf16x8 fa0, fa1, fa2, fa3, fb0, fb1, fb2, fb3;
;         {   float ps = 0.f;
; #pragma unroll
;             for (int r = 0; r < 16; ++r) { pa0[r] = __builtin_amdgcn_exp2f(pa0[r]); pa1[r] = __builtin_amdgcn_exp2f(pa1[r]);     ps += pa0[r] + pa1[r]; }
;             l0 += ps; PK4(pa0, 0, fa0); PK4(pa0, 8, fa1); PK4(pa1, 0, fa2); PK4(pa1, 8, fa3); }
;         {   float ps = 0.f;
; #pragma unroll
;             for (int r = 0; r < 16; ++r) { pb0[r] = __builtin_amdgcn_exp2f(pb0[r]); pb1[r] = __builtin_amdgcn_exp2f(pb1[r]); ps += pb0[r] + pb1[r]; }
;             l1 += ps; PK4(pb0, 0, fb0); PK4(pb0, 8, fb1); PK4(pb1, 0, fb2); PK4(pb1, 8, fb3); }
;         {   const int vb = vb0 + cur;
;     ...
;             PV2(0); PV2(1);
;     ...
;         }
;         if (t + 1 < NT) {
;             int tw = tid; asm volatile("" : "+v"(tw));
;             char* bb_ = lds + (BUF - cur);
;             *reinterpret_cast<bf16x8*>(bb_ + KN_OFF + (tw >> 3) * 144 + (tw & 7) * 16) = s_kn;
;             if (tw < 256) *reinterpret_cast<bf16x8*>(bb_ + KR_OFF + ((tw >> 2) & 63) * 80 + (tw & 3) * 16) = s_kr;
;             *reinterpret_cast<bf16x8*>(bb_ + V_OFF + v_st<2>(tw >> 3, (tw & 7) * 8)) = s_v;
;         }
;         __syncthreads();
	v_mfma_f32_32x32x16_bf16 v[0:15], v[196:199], v[96:99], v[0:15]
	v_exp_f32_e32 v115, v115
	v_add_f32_e32 v190, v190, v114
	v_exp_f32_e32 v116, v116
	v_add_f32_e32 v190, v190, v115
	v_exp_f32_e32 v117, v117
	v_mfma_f32_32x32x16_bf16 v[32:47], v[204:207], v[96:99], v[32:47]
	v_add_f32_e32 v190, v190, v116
	v_exp_f32_e32 v118, v118
	v_add_f32_e32 v190, v190, v117
	v_exp_f32_e32 v119, v119
	v_add_f32_e32 v190, v190, v118
	v_exp_f32_e32 v120, v120
	v_mfma_f32_32x32x16_bf16 v[16:31], v[196:199], v[104:107], v[16:31]
	v_add_f32_e32 v190, v190, v119
	v_exp_f32_e32 v121, v121
	v_add_f32_e32 v190, v190, v120
	v_exp_f32_e32 v122, v122
	v_add_f32_e32 v190, v190, v121
	v_mfma_f32_32x32x16_bf16 v[48:63], v[204:207], v[104:107], v[48:63]
	v_exp_f32_e32 v123, v123
	v_add_f32_e32 v190, v190, v122
	v_exp_f32_e32 v124, v124
	v_add_f32_e32 v190, v190, v123
	v_exp_f32_e32 v125, v125
	v_mfma_f32_32x32x16_bf16 v[0:15], v[200:203], v[100:103], v[0:15]
	v_add_f32_e32 v190, v190, v124
	v_exp_f32_e32 v126, v126
	v_add_f32_e32 v190, v190, v125
	v_exp_f32_e32 v127, v127
	v_add_f32_e32 v190, v190, v126
	v_add_f32_e32 v190, v190, v127
	s_waitcnt vmcnt(0)
	ds_write_b128 v184, v[180:183] offset:30976
	ds_write_b128 v188, v[176:179] offset:45312
	ds_write_b64 v189, v[186:187] offset:40192
	v_mfma_f32_32x32x16_bf16 v[32:47], v[208:211], v[100:103], v[32:47]
	v_cvt_pk_bf16_f32 v220, v112, v113
	v_cvt_pk_bf16_f32 v221, v114, v115
	v_cvt_pk_bf16_f32 v222, v116, v117
	v_cvt_pk_bf16_f32 v223, v118, v119
	v_cvt_pk_bf16_f32 v224, v120, v121
	v_cvt_pk_bf16_f32 v225, v122, v123
	v_cvt_pk_bf16_f32 v226, v124, v125
	v_cvt_pk_bf16_f32 v227, v126, v127
	v_mfma_f32_32x32x16_bf16 v[16:31], v[200:203], v[108:111], v[16:31]
	v_lshl_add_u64 v[176:177], v[194:195], 0, s[2:3]
	s_mov_b32 s12, 0x8e20000
	v_add_co_u32_e32 v178, vcc, s12, v176
	s_mov_b32 s12, 0xae20000
	s_nop 0
	v_addc_co_u32_e32 v179, vcc, 0, v177, vcc
	v_add_co_u32_e32 v176, vcc, s12, v176
	s_nop 1
	v_addc_co_u32_e32 v177, vcc, 0, v177, vcc
	global_load_dwordx4 v[180:183], v[178:179], off
	global_load_dwordx4 v[176:179], v[176:177], off
	v_lshl_add_u64 v[186:187], v[192:193], 0, s[2:3]
	global_load_dwordx2 v[186:187], v[186:187], off
	v_exp_f32_e32 v80, v80
	v_exp_f32_e32 v81, v81
	v_add_f32_e32 v191, v191, v80
	v_exp_f32_e32 v82, v82
	v_mfma_f32_32x32x16_bf16 v[48:63], v[208:211], v[108:111], v[48:63]
	v_add_f32_e32 v191, v191, v81
	v_exp_f32_e32 v83, v83
	v_add_f32_e32 v191, v191, v82
	v_exp_f32_e32 v84, v84
	v_add_f32_e32 v191, v191, v83
	s_waitcnt lgkmcnt(0)
	s_barrier
	v_mfma_f32_32x32x16_bf16 v[0:15], v[220:223], v[64:67], v[0:15]
	v_exp_f32_e32 v85, v85
	v_add_f32_e32 v191, v191, v84
	v_exp_f32_e32 v86, v86
	v_add_f32_e32 v191, v191, v85
	v_exp_f32_e32 v87, v87
	v_add_f32_e32 v191, v191, v86
	v_mfma_f32_32x32x16_bf16 v[16:31], v[220:223], v[72:75], v[16:31]
	v_exp_f32_e32 v88, v88
	v_add_f32_e32 v191, v191, v87
	v_exp_f32_e32 v89, v89
	v_add_f32_e32 v191, v191, v88
	v_exp_f32_e32 v90, v90
	v_mfma_f32_32x32x16_bf16 v[0:15], v[224:227], v[68:71], v[0:15]
	v_add_f32_e32 v191, v191, v89
	v_exp_f32_e32 v91, v91
	v_add_f32_e32 v191, v191, v90
	v_exp_f32_e32 v92, v92
	v_add_f32_e32 v191, v191, v91
	v_exp_f32_e32 v93, v93
	v_mfma_f32_32x32x16_bf16 v[16:31], v[224:227], v[76:79], v[16:31]
	v_add_f32_e32 v191, v191, v92
	v_exp_f32_e32 v94, v94
	v_add_f32_e32 v191, v191, v93
	v_exp_f32_e32 v95, v95
	v_add_f32_e32 v191, v191, v94
	v_add_f32_e32 v191, v191, v95
	v_cvt_pk_bf16_f32 v228, v80, v81
	v_cvt_pk_bf16_f32 v229, v82, v83
	v_cvt_pk_bf16_f32 v230, v84, v85
	v_cvt_pk_bf16_f32 v231, v86, v87
	v_cvt_pk_bf16_f32 v232, v88, v89
	v_cvt_pk_bf16_f32 v233, v90, v91
	v_cvt_pk_bf16_f32 v234, v92, v93
	v_cvt_pk_bf16_f32 v235, v94, v95
	s_sub_i32 s16, 0x7900, s16
	s_add_i32 s14, s14, -1
	s_cmp_eq_u32 s14, 0
	v_mfma_f32_32x32x16_bf16 v[32:47], v[228:231], v[64:67], v[32:47]
	v_mfma_f32_32x32x16_bf16 v[48:63], v[228:231], v[72:75], v[48:63]
	v_mfma_f32_32x32x16_bf16 v[32:47], v[232:235], v[68:71], v[32:47]
	v_mfma_f32_32x32x16_bf16 v[48:63], v[232:235], v[76:79], v[48:63]
	s_cbranch_scc1 .Lmla_exit
	v_mov_b32_e32 v240, 0x358637bd
	s_branch .LBB0_1629
.Lmla_exit:
	s_waitcnt vmcnt(0)
.LBB0_1633:
	v_add3_u32 v184, s15, v246, v244
	ds_read_b128 v[64:67], v184 offset:30976
	ds_read_b128 v[176:179], v184 offset:31008
	ds_read_b128 v[80:83], v184 offset:35584
	ds_read_b128 v[180:183], v184 offset:35616
	v_add3_u32 v186, s15, v245, v244
	s_waitcnt lgkmcnt(3)
	v_mfma_f32_32x32x16_bf16 v[96:111], v[64:67], v[160:163], 0
	v_mfma_f32_32x32x16_bf16 v[64:79], v[64:67], v[164:167], 0
	s_waitcnt lgkmcnt(1)
	v_mfma_f32_32x32x16_bf16 v[112:127], v[80:83], v[160:163], 0
	v_mfma_f32_32x32x16_bf16 v[80:95], v[80:83], v[164:167], 0
	v_mfma_f32_32x32x16_bf16 v[64:79], v[176:179], v[172:175], v[64:79]
	ds_read_b128 v[160:163], v184 offset:31040
	ds_read_b128 v[164:167], v184 offset:35648
	v_mfma_f32_32x32x16_bf16 v[96:111], v[176:179], v[168:171], v[96:111]
	s_waitcnt lgkmcnt(2)
	v_mfma_f32_32x32x16_bf16 v[112:127], v[180:183], v[168:171], v[112:127]
	v_mfma_f32_32x32x16_bf16 v[80:95], v[180:183], v[172:175], v[80:95]
	s_waitcnt lgkmcnt(1)
	v_mfma_f32_32x32x16_bf16 v[64:79], v[160:163], v[152:155], v[64:79]
	v_mfma_f32_32x32x16_bf16 v[96:111], v[160:163], v[156:159], v[96:111]
	s_waitcnt lgkmcnt(0)
	v_mfma_f32_32x32x16_bf16 v[112:127], v[164:167], v[156:159], v[112:127]
	ds_read_b128 v[156:159], v184 offset:31072
	ds_read_b128 v[160:163], v184 offset:35680
	v_mfma_f32_32x32x16_bf16 v[80:95], v[164:167], v[152:155], v[80:95]
	s_waitcnt lgkmcnt(1)
	v_mfma_f32_32x32x16_bf16 v[64:79], v[156:159], v[148:151], v[64:79]
	v_mfma_f32_32x32x16_bf16 v[96:111], v[156:159], v[144:147], v[96:111]
	s_waitcnt lgkmcnt(0)
; #define SBAR() __builtin_amdgcn_sched_barrier(0)
; #define SLOAD2(k0) do { s_kn = *reinterpret_cast<const bf16x8*>(Kn + (size_t)((k0) + kn_r) * 1024 + kn_c); s_kr = *reinterpret_cast<const bf16x8*>(Kr + (size_t)((k0) + kr_r) * 32 + kr_c); \
;     s_v = *reinterpret_cast<const bf16x8*>(Vh + (size_t)((k0) + kn_r) * 1024 + kn_c); } while (0)
; __device__ __forceinline__ void attn_mla2(const bf16* __restrict__ Q0, const bf16* __restrict__ Q1, const bf16* __restrict__ Kn, const bf16* __restrict__ Kr, const bf16* __restrict__ Vh, ...
;     ...
;         {
;             const char* kb = buf + KN_OFF + r32 * 144 + hi * 16; const char* kr = buf + KR_OFF + r32 * 80 + hi * 16;
;     ...
;             bf16x8 c0 = KLD0(0), c1 = KLD1(0);
; #pragma unroll
;             for (int d0 = 0; d0 < 6; ++d0) {
;                 bf16x8 n0 = c0, n1 = c1;
;                 if (d0 + 1 < 6) { n0 = KLD0(d0 + 1); n1 = KLD1(d0 + 1); }
;                 pa0 = __builtin_amdgcn_mfma_f32_32x32x16_bf16(c0, q0[d0], pa0, 0, 0, 0); pb0 = __builtin_amdgcn_mfma_f32_32x32x16_bf16(c0, q1[d0], pb0, 0, 0, 0);
;                 pa1 = __builtin_amdgcn_mfma_f32_32x32x16_bf16(c1, q0[d0], pa1, 0, 0, 0); pb1 = __builtin_amdgcn_mfma_f32_32x32x16_bf16(c1, q1[d0], pb1, 0, 0, 0);
;                 SBAR(); c0 = n0; c1 = n1;
;             }
;     ...
;         }
;         if (t + 1 < NT) SLOAD2((t + 1) * 64);
;         bf16x8 fa0, fa1, fa2, fa3, fb0, fb1, fb2, fb3;
;         {   float ps = 0.f;
; #pragma unroll
;             for (int r = 0; r < 16; ++r) { pa0[r] = __builtin_amdgcn_exp2f(pa0[r]); pa1[r] = __builtin_amdgcn_exp2f(pa1[r]);     ps += pa0[r] + pa1[r]; }
;             l0 += ps; PK4(pa0, 0, fa0); PK4(pa0, 8, fa1); PK4(pa1, 0, fa2); PK4(pa1, 8, fa3); }
;         {   float ps = 0.f;
; #pragma unroll
;             for (int r = 0; r < 16; ++r) { pb0[r] = __builtin_amdgcn_exp2f(pb0[r]); pb1[r] = __builtin_amdgcn_exp2f(pb1[r]); ps += pb0[r] + pb1[r]; }
;             l1 += ps; PK4(pb0, 0, fb0); PK4(pb0, 8, fb1); PK4(pb1, 0, fb2); PK4(pb1, 8, fb3); }
;         {   const int vb = vb0 + cur;
;     ...
;             PV2(0); PV2(1);
	v_mfma_f32_32x32x16_bf16 v[112:127], v[160:163], v[144:147], v[112:127]
	ds_read_b128 v[144:147], v186 offset:40192
	ds_read_b128 v[152:155], v186 offset:42752
	v_mfma_f32_32x32x16_bf16 v[80:95], v[160:163], v[148:151], v[80:95]
	s_waitcnt lgkmcnt(1)
	v_mfma_f32_32x32x16_bf16 v[64:79], v[144:147], v[136:139], v[64:79]
	v_mfma_f32_32x32x16_bf16 v[96:111], v[144:147], v[140:143], v[96:111]
	s_waitcnt lgkmcnt(0)
	v_mfma_f32_32x32x16_bf16 v[112:127], v[152:155], v[140:143], v[112:127]
	ds_read_b128 v[140:143], v186 offset:40224
	ds_read_b128 v[144:147], v186 offset:42784
	v_mfma_f32_32x32x16_bf16 v[80:95], v[152:155], v[136:139], v[80:95]
	s_waitcnt lgkmcnt(1)
	v_mfma_f32_32x32x16_bf16 v[64:79], v[140:143], v[132:135], v[64:79]
	v_mfma_f32_32x32x16_bf16 v[96:111], v[140:143], v[128:131], v[96:111]
	s_waitcnt lgkmcnt(0)
	v_mfma_f32_32x32x16_bf16 v[112:127], v[144:147], v[128:131], v[112:127]
	v_mfma_f32_32x32x16_bf16 v[80:95], v[144:147], v[132:135], v[80:95]
	s_nop 8
	v_exp_f32_e32 v128, v96
	s_nop 0
	v_exp_f32_e32 v112, v112
	v_exp_f32_e32 v129, v97
	v_exp_f32_e32 v113, v113
	v_exp_f32_e32 v130, v98
	v_exp_f32_e32 v114, v114
	v_exp_f32_e32 v131, v99
	v_exp_f32_e32 v115, v115
	v_exp_f32_e32 v132, v100
	v_exp_f32_e32 v116, v116
	v_exp_f32_e32 v133, v101
	v_exp_f32_e32 v117, v117
	v_exp_f32_e32 v134, v102
	v_exp_f32_e32 v118, v118
	v_exp_f32_e32 v135, v103
	v_exp_f32_e32 v119, v119
	v_exp_f32_e32 v136, v104
	v_exp_f32_e32 v120, v120
	v_exp_f32_e32 v137, v105
	v_exp_f32_e32 v121, v121
	v_exp_f32_e32 v138, v106
	v_exp_f32_e32 v122, v122
	v_exp_f32_e32 v139, v107
	v_exp_f32_e32 v123, v123
	v_exp_f32_e32 v140, v108
	v_exp_f32_e32 v124, v124
	v_exp_f32_e32 v141, v109
	v_exp_f32_e32 v125, v125
	v_exp_f32_e32 v142, v110
	v_exp_f32_e32 v126, v126
	v_exp_f32_e32 v143, v111
	v_exp_f32_e32 v127, v127
	v_cvt_pk_bf16_f32 v96, v128, v129
	v_cvt_pk_bf16_f32 v97, v130, v131
	v_cvt_pk_bf16_f32 v98, v132, v133
	v_cvt_pk_bf16_f32 v99, v134, v135
	v_cvt_pk_bf16_f32 v100, v136, v137
	v_cvt_pk_bf16_f32 v101, v138, v139
	v_cvt_pk_bf16_f32 v102, v140, v141
	v_cvt_pk_bf16_f32 v103, v142, v143
	v_cvt_pk_bf16_f32 v104, v112, v113
	v_cvt_pk_bf16_f32 v105, v114, v115
	v_cvt_pk_bf16_f32 v106, v116, v117
	v_cvt_pk_bf16_f32 v107, v118, v119
	v_cvt_pk_bf16_f32 v108, v120, v121
	v_cvt_pk_bf16_f32 v109, v122, v123
	v_cvt_pk_bf16_f32 v110, v124, v125
	v_cvt_pk_bf16_f32 v111, v126, v127
	v_exp_f32_e32 v144, v64
	v_exp_f32_e32 v145, v80
	v_exp_f32_e32 v146, v65
	v_exp_f32_e32 v147, v81
	v_exp_f32_e32 v148, v66
	v_exp_f32_e32 v149, v82
	v_exp_f32_e32 v150, v67
	v_exp_f32_e32 v151, v83
	v_exp_f32_e32 v152, v68
	v_exp_f32_e32 v153, v84
	v_exp_f32_e32 v154, v69
	v_exp_f32_e32 v155, v85
	v_exp_f32_e32 v156, v70
	v_exp_f32_e32 v157, v86
	v_exp_f32_e32 v158, v71
	v_exp_f32_e32 v159, v87
	v_exp_f32_e32 v160, v72
	v_exp_f32_e32 v161, v88
	v_exp_f32_e32 v162, v73
	v_exp_f32_e32 v163, v89
	v_exp_f32_e32 v164, v74
	v_exp_f32_e32 v165, v90
	v_exp_f32_e32 v166, v75
	v_exp_f32_e32 v167, v91
	v_exp_f32_e32 v168, v76
	v_exp_f32_e32 v169, v92
	v_exp_f32_e32 v170, v77
	v_exp_f32_e32 v171, v93
	v_exp_f32_e32 v172, v78
	v_exp_f32_e32 v173, v94
	v_exp_f32_e32 v174, v79
	v_exp_f32_e32 v175, v95
	v_cvt_pk_bf16_f32 v64, v144, v146
	v_cvt_pk_bf16_f32 v65, v148, v150
	v_cvt_pk_bf16_f32 v66, v152, v154
	v_cvt_pk_bf16_f32 v67, v156, v158
	v_cvt_pk_bf16_f32 v68, v160, v162
	v_cvt_pk_bf16_f32 v69, v164, v166
	v_cvt_pk_bf16_f32 v70, v168, v170
	v_cvt_pk_bf16_f32 v71, v172, v174
	v_cvt_pk_bf16_f32 v72, v145, v147
	v_cvt_pk_bf16_f32 v73, v149, v151
	v_cvt_pk_bf16_f32 v74, v153, v155
	v_cvt_pk_bf16_f32 v75, v157, v159
	v_cvt_pk_bf16_f32 v76, v161, v163
	v_cvt_pk_bf16_f32 v77, v165, v167
	v_cvt_pk_bf16_f32 v78, v169, v171
	v_cvt_pk_bf16_f32 v79, v173, v175
	v_add_u32_e32 v176, s16, v248
	ds_read_b64_tr_b16 v[80:81], v176 offset:0
	ds_read_b64_tr_b16 v[82:83], v176 offset:0x400
	ds_read_b64_tr_b16 v[84:85], v176 offset:0x800
	ds_read_b64_tr_b16 v[86:87], v176 offset:0xc00
	ds_read_b64_tr_b16 v[88:89], v176 offset:0x1000
	ds_read_b64_tr_b16 v[90:91], v176 offset:0x1400
	ds_read_b64_tr_b16 v[92:93], v176 offset:0x1800
	ds_read_b64_tr_b16 v[94:95], v176 offset:0x1c00
	s_waitcnt lgkmcnt(0)
	v_permlane32_swap_b32_e32 v64, v66
	v_permlane32_swap_b32_e32 v65, v67
	v_permlane32_swap_b32_e32 v96, v98
	v_permlane32_swap_b32_e32 v97, v99
	v_permlane32_swap_b32_e32 v100, v102
	v_permlane32_swap_b32_e32 v101, v103
	v_permlane32_swap_b32_e32 v104, v106
	v_permlane32_swap_b32_e32 v105, v107
	v_permlane32_swap_b32_e32 v108, v110
	v_permlane32_swap_b32_e32 v109, v111
	v_permlane32_swap_b32_e32 v68, v70
	v_permlane32_swap_b32_e32 v69, v71
	v_permlane32_swap_b32_e32 v72, v74
	v_permlane32_swap_b32_e32 v73, v75
	v_permlane32_swap_b32_e32 v76, v78
	v_permlane32_swap_b32_e32 v77, v79
	v_mfma_f32_32x32x16_bf16 v[0:15], v[96:99], v[80:83], v[0:15]
	v_mfma_f32_32x32x16_bf16 v[32:47], v[64:67], v[80:83], v[32:47]
	ds_read_b64_tr_b16 v[80:81], v176 offset:0x200
	ds_read_b64_tr_b16 v[82:83], v176 offset:0x600
	v_mfma_f32_32x32x16_bf16 v[0:15], v[100:103], v[84:87], v[0:15]
	v_mfma_f32_32x32x16_bf16 v[32:47], v[68:71], v[84:87], v[32:47]
	ds_read_b64_tr_b16 v[84:85], v176 offset:0xa00
	ds_read_b64_tr_b16 v[86:87], v176 offset:0xe00
	v_mfma_f32_32x32x16_bf16 v[0:15], v[104:107], v[88:91], v[0:15]
	v_mfma_f32_32x32x16_bf16 v[32:47], v[72:75], v[88:91], v[32:47]
	ds_read_b64_tr_b16 v[88:89], v176 offset:0x1200
	ds_read_b64_tr_b16 v[90:91], v176 offset:0x1600
	v_mfma_f32_32x32x16_bf16 v[0:15], v[108:111], v[92:95], v[0:15]
	v_mfma_f32_32x32x16_bf16 v[32:47], v[76:79], v[92:95], v[32:47]
	ds_read_b64_tr_b16 v[92:93], v176 offset:0x1a00
	ds_read_b64_tr_b16 v[94:95], v176 offset:0x1e00
	s_waitcnt lgkmcnt(0)
; __device__ __forceinline__ float add_xor32(float v) { auto rr = __builtin_amdgcn_permlane32_swap(__float_as_uint(v), __float_as_uint(v), false, false); return __uint_as_float(rr[0]) + __uint_as_float(rr[1]); }
; __device__ __forceinline__ int crow(int r, int hi) { return (r & 3) + 8 * (r >> 2) + 4 * hi; }
; template <int DVB> __device__ __forceinline__ int v_st(int k, int c) { const int kk = (k & ~0xC) | ((k & 4) << 1) | ((k & 8) >> 1); return ((kk >> 3) * DVB + (c >> 5)) * 512 + ((kk & 7) * 32 + (c & 31)) * 2; }
; __device__ __forceinline__ void attn_mla2(const bf16* __restrict__ Q0, const bf16* __restrict__ Q1, const bf16* __restrict__ Kn, const bf16* __restrict__ Kr, const bf16* __restrict__ Vh, ...
;     ...
;             for (int r = 0; r < 16; ++r) { pa0[r] = __builtin_amdgcn_exp2f(pa0[r]); pa1[r] = __builtin_amdgcn_exp2f(pa1[r]);     ps += pa0[r] + pa1[r]; }
;             l0 += ps; PK4(pa0, 0, fa0); PK4(pa0, 8, fa1); PK4(pa1, 0, fa2); PK4(pa1, 8, fa3); }
;         {   float ps = 0.f;
; #pragma unroll
;             for (int r = 0; r < 16; ++r) { pb0[r] = __builtin_amdgcn_exp2f(pb0[r]); pb1[r] = __builtin_amdgcn_exp2f(pb1[r]); ps += pb0[r] + pb1[r]; }
;             l1 += ps; PK4(pb0, 0, fb0); PK4(pb0, 8, fb1); PK4(pb1, 0, fb2); PK4(pb1, 8, fb3); }
;         {   const int vb = vb0 + cur;
;     ...
;             PV2(0); PV2(1);
;     ...
;         }
;         if (t + 1 < NT) {
;             int tw = tid; asm volatile("" : "+v"(tw));
;             char* bb_ = lds + (BUF - cur);
;             *reinterpret_cast<bf16x8*>(bb_ + KN_OFF + (tw >> 3) * 144 + (tw & 7) * 16) = s_kn;
;             if (tw < 256) *reinterpret_cast<bf16x8*>(bb_ + KR_OFF + ((tw >> 2) & 63) * 80 + (tw & 3) * 16) = s_kr;
;             *reinterpret_cast<bf16x8*>(bb_ + V_OFF + v_st<2>(tw >> 3, (tw & 7) * 8)) = s_v;
;         }
;         __syncthreads();
;         cur = BUF - cur;
;     }
;     l0 = add_xor32(l0); l1 = add_xor32(l1);
;     if (hi == 0) { wsf[r32] = l0; wsf[32 + r32] = l1; } asm volatile("s_waitcnt lgkmcnt(0)" ::: "memory");
; #pragma unroll
;     for (int r = 0; r < 16; ++r) { const float ra = __builtin_amdgcn_rcpf(wsf[crow(r, hi)]), rb = __builtin_amdgcn_rcpf(wsf[32 + crow(r, hi)]);
; #pragma unroll
;         for (int d = 0; d < 2; ++d) { o[0][d][r] *= ra; o[1][d][r] *= rb; } }
;     __syncthreads();
	v_mfma_f32_32x32x16_bf16 v[48:63], v[64:67], v[80:83], v[48:63]
	v_add_f32_e32 v64, v144, v145
	v_add_f32_e32 v64, 0, v64
	v_add_f32_e32 v65, v146, v147
	v_add_f32_e32 v64, v65, v64
	v_add_f32_e32 v65, v148, v149
	v_add_f32_e32 v64, v65, v64
	v_add_f32_e32 v65, v150, v151
	v_mfma_f32_32x32x16_bf16 v[16:31], v[96:99], v[80:83], v[16:31]
	v_add_f32_e32 v64, v65, v64
	v_add_f32_e32 v65, v152, v153
	v_add_f32_e32 v64, v65, v64
	v_add_f32_e32 v65, v154, v155
	v_add_f32_e32 v64, v65, v64
	v_add_f32_e32 v65, v156, v157
	v_add_f32_e32 v64, v65, v64
	v_add_f32_e32 v65, v158, v159
	v_add_f32_e32 v64, v65, v64
	v_add_f32_e32 v65, v160, v161
	v_add_f32_e32 v64, v65, v64
	v_add_f32_e32 v65, v162, v163
	v_add_f32_e32 v64, v65, v64
	v_add_f32_e32 v65, v164, v165
	v_add_f32_e32 v64, v65, v64
	v_add_f32_e32 v65, v166, v167
	v_mfma_f32_32x32x16_bf16 v[16:31], v[100:103], v[84:87], v[16:31]
	v_add_f32_e32 v64, v65, v64
	v_add_f32_e32 v65, v168, v169
	v_add_f32_e32 v64, v65, v64
	v_add_f32_e32 v65, v170, v171
	v_add_f32_e32 v64, v65, v64
	v_add_f32_e32 v65, v172, v173
	v_add_f32_e32 v64, v65, v64
	v_mfma_f32_32x32x16_bf16 v[48:63], v[68:71], v[84:87], v[48:63]
	v_add_f32_e32 v65, v174, v175
	v_add_f32_e32 v64, v65, v64
	v_add_f32_e32 v65, v128, v112
	v_add_f32_e32 v65, 0, v65
	v_add_f32_e32 v66, v129, v113
	v_add_f32_e32 v65, v66, v65
	v_add_f32_e32 v66, v130, v114
	v_add_f32_e32 v65, v66, v65
	v_add_f32_e32 v66, v131, v115
	v_mfma_f32_32x32x16_bf16 v[16:31], v[104:107], v[88:91], v[16:31]
	v_add_f32_e32 v65, v66, v65
	v_add_f32_e32 v66, v132, v116
	v_add_f32_e32 v65, v66, v65
	v_add_f32_e32 v66, v133, v117
	v_add_f32_e32 v65, v66, v65
	v_add_f32_e32 v66, v134, v118
	v_add_f32_e32 v65, v66, v65
	v_mfma_f32_32x32x16_bf16 v[48:63], v[72:75], v[88:91], v[48:63]
	v_add_f32_e32 v66, v135, v119
	v_add_f32_e32 v65, v66, v65
	v_add_f32_e32 v66, v136, v120
	v_add_f32_e32 v65, v66, v65
	v_add_f32_e32 v66, v137, v121
	v_add_f32_e32 v65, v66, v65
	v_add_f32_e32 v66, v138, v122
	v_add_f32_e32 v65, v66, v65
	v_add_f32_e32 v66, v139, v123
	v_mfma_f32_32x32x16_bf16 v[16:31], v[108:111], v[92:95], v[16:31]
	v_add_f32_e32 v65, v66, v65
	v_add_f32_e32 v66, v140, v124
	v_add_f32_e32 v65, v66, v65
	v_add_f32_e32 v66, v141, v125
	v_add_f32_e32 v65, v66, v65
	v_add_f32_e32 v66, v142, v126
	v_add_f32_e32 v65, v66, v65
	v_mfma_f32_32x32x16_bf16 v[48:63], v[76:79], v[92:95], v[48:63]
	v_add_f32_e32 v66, v143, v127
	v_add_f32_e32 v65, v66, v65
	v_add_f32_e32 v64, v191, v64
	v_add_f32_e32 v65, v190, v65
	v_mov_b32_e32 v66, v65
	v_mov_b32_e32 v67, v64
	s_nop 0
	v_permlane32_swap_b32_e32 v65, v66
	v_permlane32_swap_b32_e32 v64, v67
	v_cmp_gt_u32_e32 vcc, 32, v247
	s_barrier
	s_and_saveexec_b64 s[12:13], vcc
	v_add_f32_e32 v65, v65, v66
	v_add_f32_e32 v64, v64, v67
	v_lshl_add_u32 v66, v242, 2, v243
	ds_write2_b32 v66, v65, v64 offset1:32
	s_or_b64 exec, exec, s[12:13]
	s_waitcnt lgkmcnt(0)
	v_add_u32_e32 v78, v243, v244
	ds_read_b128 v[66:69], v78
	ds_read_b128 v[70:73], v78 offset:32
	ds_read_b128 v[74:77], v78 offset:128
	s_waitcnt lgkmcnt(2)
	v_rcp_f32_e32 v65, v66
	s_waitcnt lgkmcnt(0)
	v_rcp_f32_e32 v66, v74
	v_mul_f32_e32 v64, v65, v0
	v_mul_f32_e32 v65, v65, v16
	v_mul_f32_e32 v0, v66, v32
	v_rcp_f32_e32 v32, v67
	v_rcp_f32_e32 v67, v75
	v_mul_f32_e32 v16, v66, v48
	v_mul_f32_e32 v48, v32, v1
	v_mul_f32_e32 v1, v67, v33
	v_mul_f32_e32 v66, v32, v17
	v_rcp_f32_e32 v32, v68
	v_rcp_f32_e32 v33, v76
	v_mul_f32_e32 v17, v67, v49
	v_mul_f32_e32 v49, v32, v2
	v_mul_f32_e32 v2, v33, v34
	v_mul_f32_e32 v67, v32, v18
	v_mul_f32_e32 v18, v33, v50
	v_rcp_f32_e32 v32, v69
	v_rcp_f32_e32 v33, v77
	v_mul_f32_e32 v50, v32, v3
	v_mul_f32_e32 v3, v33, v35
	v_mul_f32_e32 v68, v32, v19
	v_mul_f32_e32 v19, v33, v51
	ds_read_b128 v[32:35], v78 offset:160
	v_rcp_f32_e32 v51, v70
	s_waitcnt lgkmcnt(0)
	v_rcp_f32_e32 v32, v32
	v_mul_f32_e32 v69, v51, v4
	v_mul_f32_e32 v51, v51, v20
	v_rcp_f32_e32 v33, v33
	v_mul_f32_e32 v4, v32, v36
	v_mul_f32_e32 v20, v32, v52
	v_rcp_f32_e32 v32, v71
	s_nop 0
	v_mul_f32_e32 v52, v32, v5
	v_mul_f32_e32 v5, v33, v37
	v_mul_f32_e32 v70, v32, v21
	v_mul_f32_e32 v21, v33, v53
	v_rcp_f32_e32 v32, v72
	v_rcp_f32_e32 v33, v34
	v_mul_f32_e32 v53, v32, v6
	v_mul_f32_e32 v6, v33, v38
	v_mul_f32_e32 v71, v32, v22
	v_mul_f32_e32 v22, v33, v54
	v_rcp_f32_e32 v32, v73
	v_rcp_f32_e32 v33, v35
	v_mul_f32_e32 v54, v32, v7
	v_mul_f32_e32 v7, v33, v39
	v_mul_f32_e32 v72, v32, v23
	v_mul_f32_e32 v23, v33, v55
	ds_read_b128 v[32:35], v78 offset:64
	ds_read_b128 v[36:39], v78 offset:192
	s_waitcnt lgkmcnt(1)
	v_rcp_f32_e32 v55, v32
	s_waitcnt lgkmcnt(0)
	v_rcp_f32_e32 v36, v36
	v_mul_f32_e32 v73, v55, v8
	v_rcp_f32_e32 v8, v33
	v_mul_f32_e32 v32, v36, v40
	v_mul_f32_e32 v55, v55, v24
	v_mul_f32_e32 v24, v36, v56
	v_rcp_f32_e32 v36, v37
	v_mul_f32_e32 v56, v8, v9
	v_mul_f32_e32 v74, v8, v25
	v_rcp_f32_e32 v8, v34
	v_rcp_f32_e32 v9, v38
	v_mul_f32_e32 v25, v36, v57
	v_mul_f32_e32 v33, v36, v41
	v_mul_f32_e32 v57, v8, v10
	v_mul_f32_e32 v34, v9, v42
	v_mul_f32_e32 v75, v8, v26
	v_mul_f32_e32 v26, v9, v58
	v_rcp_f32_e32 v8, v35
	v_rcp_f32_e32 v9, v39
	ds_read_b128 v[38:41], v78 offset:224
	v_mul_f32_e32 v58, v8, v11
	v_mul_f32_e32 v35, v9, v43
	v_mul_f32_e32 v76, v8, v27
	v_mul_f32_e32 v27, v9, v59
	ds_read_b128 v[8:11], v78 offset:96
	s_waitcnt lgkmcnt(1)
	v_rcp_f32_e32 v37, v38
	s_waitcnt lgkmcnt(0)
	s_barrier
; __device__ __forceinline__ void st8(bf16* p, f32x4 a, f32x4 b) { u32x4 w; w.x = cvtpk(a[0], a[1]); w.y = cvtpk(a[2], a[3]); w.z = cvtpk(b[0], b[1]); w.w = cvtpk(b[2], b[3]); *(u32x4*)p = w; }
; __device__ __forceinline__ int crow(int r, int hi) { return (r & 3) + 8 * (r >> 2) + 4 * hi; }
; __global__ void __launch_bounds__(512, 2) fwd_kernel(Args a) {
;     ...
;                         const int lane_e = tidv & 63, r32e = lane_e & 31, hie = lane_e >> 5; const size_t row0e = (size_t)b * SEQ + qb * 512 + (size_t)__builtin_amdgcn_readfirstlane(tidv >> 6) * 64;
;                         float* stg = (float*)lds + (size_t)__builtin_amdgcn_readfirstlane(tidv >> 6) * (32 * 68);
; #pragma unroll
;                         for (int rb = 0; rb < 2; ++rb) {
; #pragma unroll
;                             for (int r = 0; r < 16; ++r)
; #pragma unroll
;                                 for (int d = 0; d < 2; ++d) stg[att::crow(r, hie) * 68 + d * 32 + r32e] = o2[rb][d][r];
;                             asm volatile("s_waitcnt lgkmcnt(0)" ::: "memory");
; #pragma unroll
;                             for (int i = 0; i < 4; ++i) { const int rw = i * 8 + (lane_e >> 3), cc = (lane_e & 7) * 8;
;                                 const f32x4 v0 = *(const f32x4*)(stg + rw * 68 + cc), v1 = *(const f32x4*)(stg + rw * 68 + cc + 4);
;                                 const size_t off = (row0e + rb * 32 + rw) * 1024 + h * 64 + cc;
;                                 const u32x4 g = *(const u32x4*)(Gb + off);
;                                 const f32x4 g0 = {__uint_as_float(g.x << 16), __uint_as_float(g.x & 0xffff0000u), __uint_as_float(g.y << 16), __uint_as_float(g.y & 0xffff0000u)};
;                                 const f32x4 g1 = {__uint_as_float(g.z << 16), __uint_as_float(g.z & 0xffff0000u), __uint_as_float(g.w << 16), __uint_as_float(g.w & 0xffff0000u)};
;                                 st8(HO + off, v0 * g0, v1 * g1); }
;                             asm volatile("s_waitcnt lgkmcnt(0)" ::: "memory");
	v_rcp_f32_e32 v8, v8
	v_rcp_f32_e32 v9, v9
	v_rcp_f32_e32 v10, v10
	v_rcp_f32_e32 v11, v11
	v_mul_f32_e32 v12, v8, v12
	v_mul_f32_e32 v8, v8, v28
	v_rcp_f32_e32 v28, v39
	v_mul_f32_e32 v13, v9, v13
	v_mul_f32_e32 v9, v9, v29
	v_mul_f32_e32 v14, v10, v14
	v_mul_f32_e32 v38, v28, v45
	v_mul_f32_e32 v29, v28, v61
	v_rcp_f32_e32 v28, v40
	v_mul_f32_e32 v10, v10, v30
	v_mul_f32_e32 v59, v11, v15
	v_mul_f32_e32 v39, v28, v46
	v_mul_f32_e32 v30, v28, v62
	v_rcp_f32_e32 v28, v41
	v_readfirstlane_b32 s12, v241
	s_ashr_i32 s12, s12, 6
	s_ashr_i32 s13, s12, 31
	v_mul_f32_e32 v40, v28, v47
	v_mul_f32_e32 v11, v11, v31
	v_mul_f32_e32 v31, v28, v63
	s_lshl_b64 s[14:15], s[12:13], 6
	v_lshrrev_b32_e32 v28, 3, v241
	v_and_b32_e32 v15, 31, v241
	s_add_u32 s10, s14, s10
	s_mulk_i32 s12, 0x2200
	v_and_b32_e32 v41, 4, v28
	s_addc_u32 s11, s15, s11
	s_add_i32 s12, s12, 0
	v_lshlrev_b32_e32 v42, 2, v15
	v_mul_u32_u24_e32 v41, 0x110, v41
	v_lshlrev_b32_e32 v28, 3, v241
	v_add3_u32 v41, s12, v42, v41
	v_mul_f32_e32 v36, v37, v44
	v_bfe_u32 v15, v241, 3, 3
	v_and_b32_e32 v28, 56, v28
	v_add_u32_e32 v42, 0x800, v41
	v_add_u32_e32 v44, 0xa00, v41
	v_add_u32_e32 v43, 0x1000, v41
	v_add_u32_e32 v45, 0x1400, v41
	v_add_u32_e32 v46, 0x1800, v41
	v_mul_f32_e32 v37, v37, v60
	v_or_b32_e32 v60, s71, v28
	ds_write2_b32 v41, v64, v65 offset1:32
	ds_write2_b32 v41, v48, v66 offset0:68 offset1:100
	ds_write2_b32 v41, v49, v67 offset0:136 offset1:168
	ds_write2_b32 v41, v50, v68 offset0:204 offset1:236
	ds_write2_b32 v42, v69, v51 offset0:32 offset1:64
	ds_write2_b32 v42, v52, v70 offset0:100 offset1:132
	ds_write2_b32 v42, v53, v71 offset0:168 offset1:200
	ds_write2_b32 v44, v54, v72 offset0:108 offset1:140
	ds_write2_b32 v43, v73, v55 offset0:64 offset1:96
	ds_write2_b32 v43, v56, v74 offset0:132 offset1:164
	ds_write2_b32 v43, v57, v75 offset0:200 offset1:232
	ds_write2_b32 v45, v58, v76 offset0:12 offset1:44
	ds_write2_b32 v46, v12, v8 offset0:96 offset1:128
	ds_write2_b32 v46, v13, v9 offset0:164 offset1:196
	v_add_u32_e32 v47, 0x1a00, v41
	v_or_b32_e32 v8, s10, v15
	v_mov_b32_e32 v9, s11
	ds_write2_b32 v47, v14, v10 offset0:104 offset1:136
	v_add_u32_e32 v48, 0x1c00, v41
	v_lshlrev_b64 v[12:13], 11, v[8:9]
	v_lshlrev_b32_e32 v10, 1, v60
	v_lshl_add_u32 v77, v28, 2, s12
	s_movk_i32 s13, 0x110
	ds_write2_b32 v48, v59, v11 offset0:44 offset1:76
	v_or_b32_e32 v12, v12, v10
	v_mad_u32_u24 v28, v15, s13, v77
	s_waitcnt lgkmcnt(0)
	v_lshl_add_u64 v[58:59], s[8:9], 0, v[12:13]
	ds_read_b128 v[50:53], v28
	ds_read_b128 v[54:57], v28 offset:16
	global_load_dwordx4 v[58:61], v[58:59], off
	v_or_b32_e32 v14, 8, v15
	v_lshl_add_u64 v[12:13], s[4:5], 0, v[12:13]
	v_or_b32_e32 v8, s10, v14
	v_mad_u32_u24 v11, v14, s13, v77
	s_waitcnt vmcnt(0)
	v_lshlrev_b32_e32 v62, 16, v58
	v_and_b32_e32 v63, 0xffff0000, v58
	v_lshlrev_b32_e32 v58, 16, v59
	v_and_b32_e32 v59, 0xffff0000, v59
	v_lshlrev_b32_e32 v64, 16, v60
	v_and_b32_e32 v65, 0xffff0000, v60
	v_lshlrev_b32_e32 v60, 16, v61
	v_and_b32_e32 v61, 0xffff0000, v61
	s_waitcnt lgkmcnt(1)
	v_pk_mul_f32 v[52:53], v[52:53], v[58:59]
	v_pk_mul_f32 v[50:51], v[50:51], v[62:63]
	s_waitcnt lgkmcnt(0)
	v_pk_mul_f32 v[56:57], v[56:57], v[60:61]
	v_pk_mul_f32 v[54:55], v[54:55], v[64:65]
	v_cvt_pk_bf16_f32 v50, v50, v51
	v_cvt_pk_bf16_f32 v51, v52, v53
	s_nop 0
	v_cvt_pk_bf16_f32 v52, v54, v55
	v_cvt_pk_bf16_f32 v53, v56, v57
	global_store_dwordx4 v[12:13], v[50:53], off
	v_lshlrev_b64 v[12:13], 11, v[8:9]
	v_or_b32_e32 v12, v12, v10
	v_lshl_add_u64 v[58:59], s[8:9], 0, v[12:13]
	ds_read_b128 v[50:53], v11
	ds_read_b128 v[54:57], v11 offset:16
	global_load_dwordx4 v[58:61], v[58:59], off
	v_lshl_add_u64 v[12:13], s[4:5], 0, v[12:13]
	s_waitcnt vmcnt(0)
	v_lshlrev_b32_e32 v62, 16, v58
	v_and_b32_e32 v63, 0xffff0000, v58
	v_lshlrev_b32_e32 v58, 16, v59
	v_and_b32_e32 v59, 0xffff0000, v59
	v_lshlrev_b32_e32 v64, 16, v60
	v_and_b32_e32 v65, 0xffff0000, v60
	v_lshlrev_b32_e32 v60, 16, v61
	v_and_b32_e32 v61, 0xffff0000, v61
	s_waitcnt lgkmcnt(1)
	v_pk_mul_f32 v[52:53], v[52:53], v[58:59]
	v_pk_mul_f32 v[50:51], v[50:51], v[62:63]
	s_waitcnt lgkmcnt(0)
	v_pk_mul_f32 v[56:57], v[56:57], v[60:61]
	v_pk_mul_f32 v[54:55], v[54:55], v[64:65]
	v_cvt_pk_bf16_f32 v50, v50, v51
	v_cvt_pk_bf16_f32 v51, v52, v53
	s_nop 0
	v_cvt_pk_bf16_f32 v52, v54, v55
	v_cvt_pk_bf16_f32 v53, v56, v57
	global_store_dwordx4 v[12:13], v[50:53], off
	v_or_b32_e32 v12, 16, v15
	v_or_b32_e32 v8, s10, v12
	v_lshlrev_b64 v[62:63], 11, v[8:9]
	v_or_b32_e32 v62, v62, v10
	v_lshl_add_u64 v[58:59], s[8:9], 0, v[62:63]
	ds_read_b128 v[50:53], v11 offset:2176
	ds_read_b128 v[54:57], v11 offset:2192
	global_load_dwordx4 v[58:61], v[58:59], off
	v_or_b32_e32 v13, 24, v15
	v_lshl_add_u64 v[62:63], s[4:5], 0, v[62:63]
	v_or_b32_e32 v8, s10, v13
	s_or_b32 s10, s10, 32
	s_waitcnt vmcnt(0)
	v_lshlrev_b32_e32 v64, 16, v58
	v_and_b32_e32 v65, 0xffff0000, v58
	v_lshlrev_b32_e32 v58, 16, v59
	v_and_b32_e32 v59, 0xffff0000, v59
	v_lshlrev_b32_e32 v66, 16, v60
	v_and_b32_e32 v67, 0xffff0000, v60
	v_lshlrev_b32_e32 v60, 16, v61
	v_and_b32_e32 v61, 0xffff0000, v61
	s_waitcnt lgkmcnt(1)
	v_pk_mul_f32 v[52:53], v[52:53], v[58:59]
	v_pk_mul_f32 v[50:51], v[50:51], v[64:65]
	s_waitcnt lgkmcnt(0)
	v_pk_mul_f32 v[56:57], v[56:57], v[60:61]
	v_pk_mul_f32 v[54:55], v[54:55], v[66:67]
	v_cvt_pk_bf16_f32 v50, v50, v51
	v_cvt_pk_bf16_f32 v51, v52, v53
	s_nop 0
	v_cvt_pk_bf16_f32 v52, v54, v55
	v_cvt_pk_bf16_f32 v53, v56, v57
	global_store_dwordx4 v[62:63], v[50:53], off
	v_lshlrev_b64 v[62:63], 11, v[8:9]
	v_or_b32_e32 v62, v62, v10
	v_lshl_add_u64 v[58:59], s[8:9], 0, v[62:63]
	ds_read_b128 v[50:53], v11 offset:4352
	ds_read_b128 v[54:57], v11 offset:4368
	global_load_dwordx4 v[58:61], v[58:59], off
	v_lshl_add_u64 v[62:63], s[4:5], 0, v[62:63]
	v_or_b32_e32 v8, s10, v15
	s_waitcnt vmcnt(0)
; __device__ __forceinline__ void st8(bf16* p, f32x4 a, f32x4 b) { u32x4 w; w.x = cvtpk(a[0], a[1]); w.y = cvtpk(a[2], a[3]); w.z = cvtpk(b[0], b[1]); w.w = cvtpk(b[2], b[3]); *(u32x4*)p = w; }
; __device__ __forceinline__ int crow(int r, int hi) { return (r & 3) + 8 * (r >> 2) + 4 * hi; }
; __global__ void __launch_bounds__(512, 2) fwd_kernel(Args a) {
;     ...
;                         for (int rb = 0; rb < 2; ++rb) {
; #pragma unroll
;                             for (int r = 0; r < 16; ++r)
; #pragma unroll
;                                 for (int d = 0; d < 2; ++d) stg[att::crow(r, hie) * 68 + d * 32 + r32e] = o2[rb][d][r];
;                             asm volatile("s_waitcnt lgkmcnt(0)" ::: "memory");
; #pragma unroll
;                             for (int i = 0; i < 4; ++i) { const int rw = i * 8 + (lane_e >> 3), cc = (lane_e & 7) * 8;
;                                 const f32x4 v0 = *(const f32x4*)(stg + rw * 68 + cc), v1 = *(const f32x4*)(stg + rw * 68 + cc + 4);
;                                 const size_t off = (row0e + rb * 32 + rw) * 1024 + h * 64 + cc;
;                                 const u32x4 g = *(const u32x4*)(Gb + off);
;                                 const f32x4 g0 = {__uint_as_float(g.x << 16), __uint_as_float(g.x & 0xffff0000u), __uint_as_float(g.y << 16), __uint_as_float(g.y & 0xffff0000u)};
;                                 const f32x4 g1 = {__uint_as_float(g.z << 16), __uint_as_float(g.z & 0xffff0000u), __uint_as_float(g.w << 16), __uint_as_float(g.w & 0xffff0000u)};
;                                 st8(HO + off, v0 * g0, v1 * g1); }
;                             asm volatile("s_waitcnt lgkmcnt(0)" ::: "memory");
	v_lshlrev_b32_e32 v64, 16, v58
	v_and_b32_e32 v65, 0xffff0000, v58
	v_lshlrev_b32_e32 v58, 16, v59
	v_and_b32_e32 v59, 0xffff0000, v59
	v_lshlrev_b32_e32 v66, 16, v60
	v_and_b32_e32 v67, 0xffff0000, v60
	v_lshlrev_b32_e32 v60, 16, v61
	v_and_b32_e32 v61, 0xffff0000, v61
	s_waitcnt lgkmcnt(1)
	v_pk_mul_f32 v[52:53], v[52:53], v[58:59]
	v_pk_mul_f32 v[50:51], v[50:51], v[64:65]
	s_waitcnt lgkmcnt(0)
	v_pk_mul_f32 v[56:57], v[56:57], v[60:61]
	v_pk_mul_f32 v[54:55], v[54:55], v[66:67]
	v_cvt_pk_bf16_f32 v50, v50, v51
	v_cvt_pk_bf16_f32 v51, v52, v53
	s_nop 0
	v_cvt_pk_bf16_f32 v52, v54, v55
	v_cvt_pk_bf16_f32 v53, v56, v57
	global_store_dwordx4 v[62:63], v[50:53], off
	s_waitcnt lgkmcnt(0)
	ds_write2_b32 v41, v0, v16 offset1:32
	ds_write2_b32 v41, v1, v17 offset0:68 offset1:100
	ds_write2_b32 v41, v2, v18 offset0:136 offset1:168
	ds_write2_b32 v41, v3, v19 offset0:204 offset1:236
	ds_write2_b32 v42, v4, v20 offset0:32 offset1:64
	ds_write2_b32 v42, v5, v21 offset0:100 offset1:132
	ds_write2_b32 v42, v6, v22 offset0:168 offset1:200
	ds_write2_b32 v44, v7, v23 offset0:108 offset1:140
	ds_write2_b32 v43, v32, v24 offset0:64 offset1:96
	ds_write2_b32 v43, v33, v25 offset0:132 offset1:164
	ds_write2_b32 v43, v34, v26 offset0:200 offset1:232
	ds_write2_b32 v45, v35, v27 offset0:12 offset1:44
	ds_write2_b32 v46, v36, v37 offset0:96 offset1:128
	ds_write2_b32 v46, v38, v29 offset0:164 offset1:196
	ds_write2_b32 v47, v39, v30 offset0:104 offset1:136
	ds_write2_b32 v48, v40, v31 offset0:44 offset1:76
	v_lshlrev_b64 v[20:21], 11, v[8:9]
	v_or_b32_e32 v20, v20, v10
	s_waitcnt lgkmcnt(0)
	v_lshl_add_u64 v[16:17], s[8:9], 0, v[20:21]
	ds_read_b128 v[4:7], v28
	ds_read_b128 v[0:3], v28 offset:16
	global_load_dwordx4 v[16:19], v[16:17], off
	v_or_b32_e32 v8, s10, v14
	v_lshl_add_u64 v[20:21], s[4:5], 0, v[20:21]
	s_waitcnt vmcnt(0)
	v_lshlrev_b32_e32 v22, 16, v16
	v_and_b32_e32 v23, 0xffff0000, v16
	v_lshlrev_b32_e32 v16, 16, v17
	v_and_b32_e32 v17, 0xffff0000, v17
	v_lshlrev_b32_e32 v24, 16, v18
	v_and_b32_e32 v25, 0xffff0000, v18
	v_lshlrev_b32_e32 v18, 16, v19
	v_and_b32_e32 v19, 0xffff0000, v19
	s_waitcnt lgkmcnt(1)
	v_pk_mul_f32 v[6:7], v[6:7], v[16:17]
	s_waitcnt lgkmcnt(0)
	v_pk_mul_f32 v[16:17], v[2:3], v[18:19]
	v_lshlrev_b64 v[18:19], 11, v[8:9]
	v_pk_mul_f32 v[2:3], v[0:1], v[24:25]
	v_or_b32_e32 v18, v18, v10
	v_pk_mul_f32 v[4:5], v[4:5], v[22:23]
	v_lshl_add_u64 v[14:15], s[8:9], 0, v[18:19]
	v_cvt_pk_bf16_f32 v0, v4, v5
	v_cvt_pk_bf16_f32 v1, v6, v7
	v_cvt_pk_bf16_f32 v2, v2, v3
	v_cvt_pk_bf16_f32 v3, v16, v17
	global_store_dwordx4 v[20:21], v[0:3], off
	ds_read_b128 v[0:3], v11
	ds_read_b128 v[4:7], v11 offset:16
	global_load_dwordx4 v[14:17], v[14:15], off
	v_lshl_add_u64 v[18:19], s[4:5], 0, v[18:19]
	v_or_b32_e32 v8, s10, v12
	s_waitcnt vmcnt(0)
	v_lshlrev_b32_e32 v20, 16, v14
	v_and_b32_e32 v21, 0xffff0000, v14
	v_lshlrev_b32_e32 v14, 16, v15
	v_and_b32_e32 v15, 0xffff0000, v15
	v_lshlrev_b32_e32 v22, 16, v16
	v_and_b32_e32 v23, 0xffff0000, v16
	v_lshlrev_b32_e32 v16, 16, v17
	v_and_b32_e32 v17, 0xffff0000, v17
	s_waitcnt lgkmcnt(1)
	v_pk_mul_f32 v[2:3], v[2:3], v[14:15]
	v_pk_mul_f32 v[0:1], v[0:1], v[20:21]
	s_waitcnt lgkmcnt(0)
	v_pk_mul_f32 v[6:7], v[6:7], v[16:17]
	v_pk_mul_f32 v[4:5], v[4:5], v[22:23]
	v_cvt_pk_bf16_f32 v0, v0, v1
	v_cvt_pk_bf16_f32 v1, v2, v3
	s_nop 0
	v_cvt_pk_bf16_f32 v2, v4, v5
	v_cvt_pk_bf16_f32 v3, v6, v7
	global_store_dwordx4 v[18:19], v[0:3], off
	v_lshlrev_b64 v[18:19], 11, v[8:9]
	v_or_b32_e32 v18, v18, v10
	v_lshl_add_u64 v[14:15], s[8:9], 0, v[18:19]
	ds_read_b128 v[0:3], v11 offset:2176
	ds_read_b128 v[4:7], v11 offset:2192
	global_load_dwordx4 v[14:17], v[14:15], off
	v_or_b32_e32 v8, s10, v13
	v_lshlrev_b64 v[12:13], 11, v[8:9]
	v_lshl_add_u64 v[18:19], s[4:5], 0, v[18:19]
	v_or_b32_e32 v12, v12, v10
	v_lshl_add_u64 v[8:9], s[8:9], 0, v[12:13]
	v_lshl_add_u64 v[12:13], s[4:5], 0, v[12:13]
	s_waitcnt vmcnt(0)
	v_lshlrev_b32_e32 v20, 16, v14
	v_and_b32_e32 v21, 0xffff0000, v14
	v_lshlrev_b32_e32 v14, 16, v15
	v_and_b32_e32 v15, 0xffff0000, v15
	v_lshlrev_b32_e32 v22, 16, v16
	v_and_b32_e32 v23, 0xffff0000, v16
	v_lshlrev_b32_e32 v16, 16, v17
	v_and_b32_e32 v17, 0xffff0000, v17
	s_waitcnt lgkmcnt(1)
	v_pk_mul_f32 v[2:3], v[2:3], v[14:15]
	v_pk_mul_f32 v[0:1], v[0:1], v[20:21]
	s_waitcnt lgkmcnt(0)
	v_pk_mul_f32 v[6:7], v[6:7], v[16:17]
	v_pk_mul_f32 v[4:5], v[4:5], v[22:23]
	v_cvt_pk_bf16_f32 v0, v0, v1
	v_cvt_pk_bf16_f32 v1, v2, v3
	s_nop 0
	v_cvt_pk_bf16_f32 v2, v4, v5
	v_cvt_pk_bf16_f32 v3, v6, v7
	global_store_dwordx4 v[18:19], v[0:3], off
	ds_read_b128 v[4:7], v11 offset:4352
	ds_read_b128 v[0:3], v11 offset:4368
	global_load_dwordx4 v[8:11], v[8:9], off
	s_waitcnt vmcnt(0)
	v_lshlrev_b32_e32 v14, 16, v8
	v_and_b32_e32 v15, 0xffff0000, v8
	v_lshlrev_b32_e32 v8, 16, v9
	v_and_b32_e32 v9, 0xffff0000, v9
	v_lshlrev_b32_e32 v16, 16, v10
	v_and_b32_e32 v17, 0xffff0000, v10
	v_lshlrev_b32_e32 v10, 16, v11
	v_and_b32_e32 v11, 0xffff0000, v11
	s_waitcnt lgkmcnt(1)
	v_pk_mul_f32 v[6:7], v[6:7], v[8:9]
	s_waitcnt lgkmcnt(0)
	v_pk_mul_f32 v[8:9], v[2:3], v[10:11]
	v_pk_mul_f32 v[2:3], v[0:1], v[16:17]
	v_pk_mul_f32 v[4:5], v[4:5], v[14:15]
	s_nop 0
	v_cvt_pk_bf16_f32 v0, v4, v5
	v_cvt_pk_bf16_f32 v1, v6, v7
	v_cvt_pk_bf16_f32 v2, v2, v3
	v_cvt_pk_bf16_f32 v3, v8, v9
	global_store_dwordx4 v[12:13], v[0:3], off
	s_waitcnt lgkmcnt(0)
